# mLSTM post-loop head-norm/gate of the last chunk uses the batched DPP version (was serial 8-row code with ds_bpermute sums)
# baseline (speedup 1.0000x reference)
.LBB0_135:
	v_lshlrev_b32_e32 v96, 3, v222
	v_and_b32_e32 v96, 0x1f8, v96
	s_waitcnt vmcnt(0)
	s_sub_i32 s12, s82, 64
	s_add_u32 s12, s18, s12
	s_addc_u32 s13, s19, 0
	s_add_i32 s15, 0, 0x18400
	v_add_u32_e32 v65, s15, v96
	v_add_u32_e32 v64, s16, v65
	v_add_u32_e32 v66, s3, v65
	ds_read_b64 v[232:233], v64
	ds_read_b64 v[234:235], v66
	ds_read_b64 v[236:237], v66 offset:528
	ds_read_b64 v[238:239], v66 offset:1056
	ds_read_b64 v[240:241], v66 offset:1584
	ds_read_b64 v[242:243], v66 offset:2112
	ds_read_b64 v[244:245], v66 offset:2640
	ds_read_b64 v[246:247], v66 offset:3168
	v_lshl_add_u64 v[248:249], s[46:47], 0, v[96:97]
	v_lshlrev_b32_e32 v72, 16, v206
	v_and_b32_e32 v73, 0xffff0000, v206
	v_lshlrev_b32_e32 v74, 16, v207
	v_and_b32_e32 v75, 0xffff0000, v207
	v_mul_f32_e32 v72, 0xbfb8aa3b, v72
	v_mul_f32_e32 v73, 0xbfb8aa3b, v73
	v_mul_f32_e32 v74, 0xbfb8aa3b, v74
	v_mul_f32_e32 v75, 0xbfb8aa3b, v75
	v_exp_f32_e32 v72, v72
	v_exp_f32_e32 v73, v73
	v_exp_f32_e32 v74, v74
	v_exp_f32_e32 v75, v75
	v_add_f32_e32 v72, 1.0, v72
	v_add_f32_e32 v73, 1.0, v73
	v_add_f32_e32 v74, 1.0, v74
	v_add_f32_e32 v75, 1.0, v75
	v_rcp_f32_e32 v72, v72
	v_rcp_f32_e32 v73, v73
	v_rcp_f32_e32 v74, v74
	v_rcp_f32_e32 v75, v75
	v_lshlrev_b32_e32 v76, 16, v204
	v_and_b32_e32 v77, 0xffff0000, v204
	v_lshlrev_b32_e32 v78, 16, v205
	v_and_b32_e32 v79, 0xffff0000, v205
	v_mul_f32_e32 v76, 0xbfb8aa3b, v76
	v_mul_f32_e32 v77, 0xbfb8aa3b, v77
	v_mul_f32_e32 v78, 0xbfb8aa3b, v78
	v_mul_f32_e32 v79, 0xbfb8aa3b, v79
	v_exp_f32_e32 v76, v76
	v_exp_f32_e32 v77, v77
	v_exp_f32_e32 v78, v78
	v_exp_f32_e32 v79, v79
	v_add_f32_e32 v76, 1.0, v76
	v_add_f32_e32 v77, 1.0, v77
	v_add_f32_e32 v78, 1.0, v78
	v_add_f32_e32 v79, 1.0, v79
	v_rcp_f32_e32 v76, v76
	v_rcp_f32_e32 v77, v77
	v_rcp_f32_e32 v78, v78
	v_rcp_f32_e32 v79, v79
	v_lshlrev_b32_e32 v80, 16, v202
	v_and_b32_e32 v81, 0xffff0000, v202
	v_lshlrev_b32_e32 v82, 16, v203
	v_and_b32_e32 v83, 0xffff0000, v203
	v_mul_f32_e32 v80, 0xbfb8aa3b, v80
	v_mul_f32_e32 v81, 0xbfb8aa3b, v81
	v_mul_f32_e32 v82, 0xbfb8aa3b, v82
	v_mul_f32_e32 v83, 0xbfb8aa3b, v83
	v_exp_f32_e32 v80, v80
	v_exp_f32_e32 v81, v81
	v_exp_f32_e32 v82, v82
	v_exp_f32_e32 v83, v83
	v_add_f32_e32 v80, 1.0, v80
	v_add_f32_e32 v81, 1.0, v81
	v_add_f32_e32 v82, 1.0, v82
	v_add_f32_e32 v83, 1.0, v83
	v_rcp_f32_e32 v80, v80
	v_rcp_f32_e32 v81, v81
	v_rcp_f32_e32 v82, v82
	v_rcp_f32_e32 v83, v83
	v_lshlrev_b32_e32 v84, 16, v200
	v_and_b32_e32 v85, 0xffff0000, v200
	v_lshlrev_b32_e32 v86, 16, v201
	v_and_b32_e32 v87, 0xffff0000, v201
	v_mul_f32_e32 v84, 0xbfb8aa3b, v84
	v_mul_f32_e32 v85, 0xbfb8aa3b, v85
	v_mul_f32_e32 v86, 0xbfb8aa3b, v86
	v_mul_f32_e32 v87, 0xbfb8aa3b, v87
	v_exp_f32_e32 v84, v84
	v_exp_f32_e32 v85, v85
	v_exp_f32_e32 v86, v86
	v_exp_f32_e32 v87, v87
	v_add_f32_e32 v84, 1.0, v84
	v_add_f32_e32 v85, 1.0, v85
	v_add_f32_e32 v86, 1.0, v86
	v_add_f32_e32 v87, 1.0, v87
	v_rcp_f32_e32 v84, v84
	v_rcp_f32_e32 v85, v85
	v_rcp_f32_e32 v86, v86
	v_rcp_f32_e32 v87, v87
	v_lshlrev_b32_e32 v88, 16, v198
	v_and_b32_e32 v89, 0xffff0000, v198
	v_lshlrev_b32_e32 v90, 16, v199
	v_and_b32_e32 v91, 0xffff0000, v199
	v_mul_f32_e32 v88, 0xbfb8aa3b, v88
	v_mul_f32_e32 v89, 0xbfb8aa3b, v89
	v_mul_f32_e32 v90, 0xbfb8aa3b, v90
	v_mul_f32_e32 v91, 0xbfb8aa3b, v91
	v_exp_f32_e32 v88, v88
	v_exp_f32_e32 v89, v89
	v_exp_f32_e32 v90, v90
	v_exp_f32_e32 v91, v91
	v_add_f32_e32 v88, 1.0, v88
	v_add_f32_e32 v89, 1.0, v89
	v_add_f32_e32 v90, 1.0, v90
	v_add_f32_e32 v91, 1.0, v91
	v_rcp_f32_e32 v88, v88
	v_rcp_f32_e32 v89, v89
	v_rcp_f32_e32 v90, v90
	v_rcp_f32_e32 v91, v91
	v_lshlrev_b32_e32 v92, 16, v196
	v_and_b32_e32 v93, 0xffff0000, v196
	v_lshlrev_b32_e32 v94, 16, v197
	v_and_b32_e32 v95, 0xffff0000, v197
	v_mul_f32_e32 v92, 0xbfb8aa3b, v92
	v_mul_f32_e32 v93, 0xbfb8aa3b, v93
	v_mul_f32_e32 v94, 0xbfb8aa3b, v94
	v_mul_f32_e32 v95, 0xbfb8aa3b, v95
	v_exp_f32_e32 v92, v92
	v_exp_f32_e32 v93, v93
	v_exp_f32_e32 v94, v94
	v_exp_f32_e32 v95, v95
	v_add_f32_e32 v92, 1.0, v92
	v_add_f32_e32 v93, 1.0, v93
	v_add_f32_e32 v94, 1.0, v94
	v_add_f32_e32 v95, 1.0, v95
	v_rcp_f32_e32 v92, v92
	v_rcp_f32_e32 v93, v93
	v_rcp_f32_e32 v94, v94
	v_rcp_f32_e32 v95, v95
	v_lshlrev_b32_e32 v156, 16, v194
	v_and_b32_e32 v157, 0xffff0000, v194
	v_lshlrev_b32_e32 v158, 16, v195
	v_and_b32_e32 v159, 0xffff0000, v195
	v_mul_f32_e32 v156, 0xbfb8aa3b, v156
	v_mul_f32_e32 v157, 0xbfb8aa3b, v157
	v_mul_f32_e32 v158, 0xbfb8aa3b, v158
	v_mul_f32_e32 v159, 0xbfb8aa3b, v159
	v_exp_f32_e32 v156, v156
	v_exp_f32_e32 v157, v157
	v_exp_f32_e32 v158, v158
	v_exp_f32_e32 v159, v159
	v_add_f32_e32 v156, 1.0, v156
	v_add_f32_e32 v157, 1.0, v157
	v_add_f32_e32 v158, 1.0, v158
	v_add_f32_e32 v159, 1.0, v159
	v_rcp_f32_e32 v156, v156
	v_rcp_f32_e32 v157, v157
	v_rcp_f32_e32 v158, v158
	v_rcp_f32_e32 v159, v159
	v_lshlrev_b32_e32 v160, 16, v192
	v_and_b32_e32 v161, 0xffff0000, v192
	v_lshlrev_b32_e32 v162, 16, v193
	v_and_b32_e32 v163, 0xffff0000, v193
	v_mul_f32_e32 v160, 0xbfb8aa3b, v160
	v_mul_f32_e32 v161, 0xbfb8aa3b, v161
	v_mul_f32_e32 v162, 0xbfb8aa3b, v162
	v_mul_f32_e32 v163, 0xbfb8aa3b, v163
	v_exp_f32_e32 v160, v160
	v_exp_f32_e32 v161, v161
	v_exp_f32_e32 v162, v162
	v_exp_f32_e32 v163, v163
	v_add_f32_e32 v160, 1.0, v160
	v_add_f32_e32 v161, 1.0, v161
	v_add_f32_e32 v162, 1.0, v162
	v_add_f32_e32 v163, 1.0, v163
	v_rcp_f32_e32 v160, v160
	v_rcp_f32_e32 v161, v161
	v_rcp_f32_e32 v162, v162
	v_rcp_f32_e32 v163, v163
	s_waitcnt lgkmcnt(0)
	v_lshlrev_b32_e32 v64, 16, v232
	v_and_b32_e32 v65, 0xffff0000, v232
	v_lshlrev_b32_e32 v66, 16, v233
	v_and_b32_e32 v67, 0xffff0000, v233
	v_mul_f32_e32 v65, v65, v65
	v_mul_f32_e32 v67, v67, v67
	v_fma_f32 v65, v64, v64, v65
	v_fma_f32 v67, v66, v66, v67
	v_add_f32_e32 v164, v65, v67
	v_lshlrev_b32_e32 v64, 16, v234
	v_and_b32_e32 v65, 0xffff0000, v234
	v_lshlrev_b32_e32 v66, 16, v235
	v_and_b32_e32 v67, 0xffff0000, v235
	v_mul_f32_e32 v65, v65, v65
	v_mul_f32_e32 v67, v67, v67
	v_fma_f32 v65, v64, v64, v65
	v_fma_f32 v67, v66, v66, v67
	v_add_f32_e32 v165, v65, v67
	v_lshlrev_b32_e32 v64, 16, v236
	v_and_b32_e32 v65, 0xffff0000, v236
	v_lshlrev_b32_e32 v66, 16, v237
	v_and_b32_e32 v67, 0xffff0000, v237
	v_mul_f32_e32 v65, v65, v65
	v_mul_f32_e32 v67, v67, v67
	v_fma_f32 v65, v64, v64, v65
	v_fma_f32 v67, v66, v66, v67
	v_add_f32_e32 v166, v65, v67
	v_lshlrev_b32_e32 v64, 16, v238
	v_and_b32_e32 v65, 0xffff0000, v238
	v_lshlrev_b32_e32 v66, 16, v239
	v_and_b32_e32 v67, 0xffff0000, v239
	v_mul_f32_e32 v65, v65, v65
	v_mul_f32_e32 v67, v67, v67
	v_fma_f32 v65, v64, v64, v65
	v_fma_f32 v67, v66, v66, v67
	v_add_f32_e32 v167, v65, v67
	v_lshlrev_b32_e32 v64, 16, v240
	v_and_b32_e32 v65, 0xffff0000, v240
	v_lshlrev_b32_e32 v66, 16, v241
	v_and_b32_e32 v67, 0xffff0000, v241
	v_mul_f32_e32 v65, v65, v65
	v_mul_f32_e32 v67, v67, v67
	v_fma_f32 v65, v64, v64, v65
	v_fma_f32 v67, v66, v66, v67
	v_add_f32_e32 v170, v65, v67
	v_lshlrev_b32_e32 v64, 16, v242
	v_and_b32_e32 v65, 0xffff0000, v242
	v_lshlrev_b32_e32 v66, 16, v243
	v_and_b32_e32 v67, 0xffff0000, v243
	v_mul_f32_e32 v65, v65, v65
	v_mul_f32_e32 v67, v67, v67
	v_fma_f32 v65, v64, v64, v65
	v_fma_f32 v67, v66, v66, v67
	v_add_f32_e32 v171, v65, v67
	v_lshlrev_b32_e32 v64, 16, v244
	v_and_b32_e32 v65, 0xffff0000, v244
	v_lshlrev_b32_e32 v66, 16, v245
	v_and_b32_e32 v67, 0xffff0000, v245
	v_mul_f32_e32 v65, v65, v65
	v_mul_f32_e32 v67, v67, v67
	v_fma_f32 v65, v64, v64, v65
	v_fma_f32 v67, v66, v66, v67
	v_add_f32_e32 v172, v65, v67
	v_lshlrev_b32_e32 v64, 16, v246
	v_and_b32_e32 v65, 0xffff0000, v246
	v_lshlrev_b32_e32 v66, 16, v247
	v_and_b32_e32 v67, 0xffff0000, v247
	v_mul_f32_e32 v65, v65, v65
	v_mul_f32_e32 v67, v67, v67
	v_fma_f32 v65, v64, v64, v65
	v_fma_f32 v67, v66, v66, v67
	v_add_f32_e32 v173, v65, v67
	s_nop 1
	v_add_f32_dpp v164, v164, v164 quad_perm:[1,0,3,2] row_mask:0xf bank_mask:0xf
	v_add_f32_dpp v165, v165, v165 quad_perm:[1,0,3,2] row_mask:0xf bank_mask:0xf
	v_add_f32_dpp v166, v166, v166 quad_perm:[1,0,3,2] row_mask:0xf bank_mask:0xf
	v_add_f32_dpp v167, v167, v167 quad_perm:[1,0,3,2] row_mask:0xf bank_mask:0xf
	v_add_f32_dpp v170, v170, v170 quad_perm:[1,0,3,2] row_mask:0xf bank_mask:0xf
	v_add_f32_dpp v171, v171, v171 quad_perm:[1,0,3,2] row_mask:0xf bank_mask:0xf
	v_add_f32_dpp v172, v172, v172 quad_perm:[1,0,3,2] row_mask:0xf bank_mask:0xf
	v_add_f32_dpp v173, v173, v173 quad_perm:[1,0,3,2] row_mask:0xf bank_mask:0xf
	v_add_f32_dpp v164, v164, v164 quad_perm:[2,3,0,1] row_mask:0xf bank_mask:0xf
	v_add_f32_dpp v165, v165, v165 quad_perm:[2,3,0,1] row_mask:0xf bank_mask:0xf
	v_add_f32_dpp v166, v166, v166 quad_perm:[2,3,0,1] row_mask:0xf bank_mask:0xf
	v_add_f32_dpp v167, v167, v167 quad_perm:[2,3,0,1] row_mask:0xf bank_mask:0xf
	v_add_f32_dpp v170, v170, v170 quad_perm:[2,3,0,1] row_mask:0xf bank_mask:0xf
	v_add_f32_dpp v171, v171, v171 quad_perm:[2,3,0,1] row_mask:0xf bank_mask:0xf
	v_add_f32_dpp v172, v172, v172 quad_perm:[2,3,0,1] row_mask:0xf bank_mask:0xf
	v_add_f32_dpp v173, v173, v173 quad_perm:[2,3,0,1] row_mask:0xf bank_mask:0xf
	v_add_f32_dpp v164, v164, v164 row_half_mirror row_mask:0xf bank_mask:0xf
	v_add_f32_dpp v165, v165, v165 row_half_mirror row_mask:0xf bank_mask:0xf
	v_add_f32_dpp v166, v166, v166 row_half_mirror row_mask:0xf bank_mask:0xf
	v_add_f32_dpp v167, v167, v167 row_half_mirror row_mask:0xf bank_mask:0xf
	v_add_f32_dpp v170, v170, v170 row_half_mirror row_mask:0xf bank_mask:0xf
	v_add_f32_dpp v171, v171, v171 row_half_mirror row_mask:0xf bank_mask:0xf
	v_add_f32_dpp v172, v172, v172 row_half_mirror row_mask:0xf bank_mask:0xf
	v_add_f32_dpp v173, v173, v173 row_half_mirror row_mask:0xf bank_mask:0xf
	v_add_f32_dpp v164, v164, v164 row_ror:8 row_mask:0xf bank_mask:0xf
	v_add_f32_dpp v165, v165, v165 row_ror:8 row_mask:0xf bank_mask:0xf
	v_add_f32_dpp v166, v166, v166 row_ror:8 row_mask:0xf bank_mask:0xf
	v_add_f32_dpp v167, v167, v167 row_ror:8 row_mask:0xf bank_mask:0xf
	v_add_f32_dpp v170, v170, v170 row_ror:8 row_mask:0xf bank_mask:0xf
	v_add_f32_dpp v171, v171, v171 row_ror:8 row_mask:0xf bank_mask:0xf
	v_add_f32_dpp v172, v172, v172 row_ror:8 row_mask:0xf bank_mask:0xf
	v_add_f32_dpp v173, v173, v173 row_ror:8 row_mask:0xf bank_mask:0xf
	v_mov_b32_e32 v174, v164
	v_mov_b32_e32 v175, v165
	v_mov_b32_e32 v176, v166
	v_mov_b32_e32 v177, v167
	v_mov_b32_e32 v216, v170
	v_mov_b32_e32 v217, v171
	v_mov_b32_e32 v218, v172
	v_mov_b32_e32 v219, v173
	v_permlane16_swap_b32_e32 v174, v164
	v_permlane16_swap_b32_e32 v175, v165
	v_permlane16_swap_b32_e32 v176, v166
	v_permlane16_swap_b32_e32 v177, v167
	v_permlane16_swap_b32_e32 v216, v170
	v_permlane16_swap_b32_e32 v217, v171
	v_permlane16_swap_b32_e32 v218, v172
	v_permlane16_swap_b32_e32 v219, v173
	v_add_f32_e32 v164, v164, v174
	v_add_f32_e32 v165, v165, v175
	v_add_f32_e32 v166, v166, v176
	v_add_f32_e32 v167, v167, v177
	v_add_f32_e32 v170, v170, v216
	v_add_f32_e32 v171, v171, v217
	v_add_f32_e32 v172, v172, v218
	v_add_f32_e32 v173, v173, v219
	v_mov_b32_e32 v174, v164
	v_mov_b32_e32 v175, v165
	v_mov_b32_e32 v176, v166
	v_mov_b32_e32 v177, v167
	v_mov_b32_e32 v216, v170
	v_mov_b32_e32 v217, v171
	v_mov_b32_e32 v218, v172
	v_mov_b32_e32 v219, v173
	v_permlane32_swap_b32_e32 v174, v164
	v_permlane32_swap_b32_e32 v175, v165
	v_permlane32_swap_b32_e32 v176, v166
	v_permlane32_swap_b32_e32 v177, v167
	v_permlane32_swap_b32_e32 v216, v170
	v_permlane32_swap_b32_e32 v217, v171
	v_permlane32_swap_b32_e32 v218, v172
	v_permlane32_swap_b32_e32 v219, v173
	v_add_f32_e32 v164, v164, v174
	v_add_f32_e32 v165, v165, v175
	v_add_f32_e32 v166, v166, v176
	v_add_f32_e32 v167, v167, v177
	v_add_f32_e32 v170, v170, v216
	v_add_f32_e32 v171, v171, v217
	v_add_f32_e32 v172, v172, v218
	v_add_f32_e32 v173, v173, v219
	v_fmamk_f32 v169, v164, 0x3b800000, v225
	v_mul_f32_e32 v220, 0x4b800000, v169
	v_cmp_gt_f32_e32 vcc, s30, v169
	v_lshlrev_b32_e32 v64, 16, v232
	v_and_b32_e32 v65, 0xffff0000, v232
	v_cndmask_b32_e32 v169, v169, v220, vcc
	v_rsq_f32_e32 v169, v169
	v_lshlrev_b32_e32 v66, 16, v233
	v_and_b32_e32 v67, 0xffff0000, v233
	v_mul_f32_e32 v220, 0x45800000, v169
	v_cndmask_b32_e32 v70, v169, v220, vcc
	v_pk_mul_f32 v[64:65], v[72:73], v[64:65]
	v_pk_mul_f32 v[66:67], v[74:75], v[66:67]
	v_pk_mul_f32 v[64:65], v[64:65], v[70:71] op_sel_hi:[1,0]
	v_pk_mul_f32 v[66:67], v[66:67], v[70:71] op_sel_hi:[1,0]
	v_pk_mul_f32 v[64:65], v[152:153], v[64:65]
	v_pk_mul_f32 v[66:67], v[154:155], v[66:67]
	s_add_u32 s42, s12, s63
	s_addc_u32 s43, s13, 0
	s_lshl_b64 s[42:43], s[42:43], 11
	v_cvt_pk_bf16_f32 v216, v64, v65
	v_cvt_pk_bf16_f32 v217, v66, v67
	v_lshl_add_u64 v[174:175], v[248:249], 0, s[42:43]
	global_store_dwordx2 v[174:175], v[216:217], off sc1
	v_fmamk_f32 v169, v165, 0x3b800000, v225
	v_mul_f32_e32 v220, 0x4b800000, v169
	v_cmp_gt_f32_e32 vcc, s30, v169
	v_lshlrev_b32_e32 v64, 16, v234
	v_and_b32_e32 v65, 0xffff0000, v234
	v_cndmask_b32_e32 v169, v169, v220, vcc
	v_rsq_f32_e32 v169, v169
	v_lshlrev_b32_e32 v66, 16, v235
	v_and_b32_e32 v67, 0xffff0000, v235
	v_mul_f32_e32 v220, 0x45800000, v169
	v_cndmask_b32_e32 v70, v169, v220, vcc
	v_pk_mul_f32 v[64:65], v[76:77], v[64:65]
	v_pk_mul_f32 v[66:67], v[78:79], v[66:67]
	v_pk_mul_f32 v[64:65], v[64:65], v[70:71] op_sel_hi:[1,0]
	v_pk_mul_f32 v[66:67], v[66:67], v[70:71] op_sel_hi:[1,0]
	v_pk_mul_f32 v[64:65], v[152:153], v[64:65]
	v_pk_mul_f32 v[66:67], v[154:155], v[66:67]
	s_add_u32 s42, s12, s92
	s_addc_u32 s43, s13, 0
	s_lshl_b64 s[42:43], s[42:43], 11
	v_cvt_pk_bf16_f32 v218, v64, v65
	v_cvt_pk_bf16_f32 v219, v66, v67
	v_lshl_add_u64 v[176:177], v[248:249], 0, s[42:43]
	global_store_dwordx2 v[176:177], v[218:219], off sc1
	v_fmamk_f32 v169, v166, 0x3b800000, v225
	v_mul_f32_e32 v220, 0x4b800000, v169
	v_cmp_gt_f32_e32 vcc, s30, v169
	v_lshlrev_b32_e32 v64, 16, v236
	v_and_b32_e32 v65, 0xffff0000, v236
	v_cndmask_b32_e32 v169, v169, v220, vcc
	v_rsq_f32_e32 v169, v169
	v_lshlrev_b32_e32 v66, 16, v237
	v_and_b32_e32 v67, 0xffff0000, v237
	v_mul_f32_e32 v220, 0x45800000, v169
	v_cndmask_b32_e32 v70, v169, v220, vcc
	v_pk_mul_f32 v[64:65], v[80:81], v[64:65]
	v_pk_mul_f32 v[66:67], v[82:83], v[66:67]
	v_pk_mul_f32 v[64:65], v[64:65], v[70:71] op_sel_hi:[1,0]
	v_pk_mul_f32 v[66:67], v[66:67], v[70:71] op_sel_hi:[1,0]
	v_pk_mul_f32 v[64:65], v[152:153], v[64:65]
	v_pk_mul_f32 v[66:67], v[154:155], v[66:67]
	s_add_u32 s42, s12, s54
	s_addc_u32 s43, s13, 0
	s_lshl_b64 s[42:43], s[42:43], 11
	v_cvt_pk_bf16_f32 v216, v64, v65
	v_cvt_pk_bf16_f32 v217, v66, v67
	v_lshl_add_u64 v[174:175], v[248:249], 0, s[42:43]
	global_store_dwordx2 v[174:175], v[216:217], off sc1
	v_fmamk_f32 v169, v167, 0x3b800000, v225
	v_mul_f32_e32 v220, 0x4b800000, v169
	v_cmp_gt_f32_e32 vcc, s30, v169
	v_lshlrev_b32_e32 v64, 16, v238
	v_and_b32_e32 v65, 0xffff0000, v238
	v_cndmask_b32_e32 v169, v169, v220, vcc
	v_rsq_f32_e32 v169, v169
	v_lshlrev_b32_e32 v66, 16, v239
	v_and_b32_e32 v67, 0xffff0000, v239
	v_mul_f32_e32 v220, 0x45800000, v169
	v_cndmask_b32_e32 v70, v169, v220, vcc
	v_pk_mul_f32 v[64:65], v[84:85], v[64:65]
	v_pk_mul_f32 v[66:67], v[86:87], v[66:67]
	v_pk_mul_f32 v[64:65], v[64:65], v[70:71] op_sel_hi:[1,0]
	v_pk_mul_f32 v[66:67], v[66:67], v[70:71] op_sel_hi:[1,0]
	v_pk_mul_f32 v[64:65], v[152:153], v[64:65]
	v_pk_mul_f32 v[66:67], v[154:155], v[66:67]
	s_add_u32 s42, s12, s5
	s_addc_u32 s43, s13, 0
	s_lshl_b64 s[42:43], s[42:43], 11
	v_cvt_pk_bf16_f32 v218, v64, v65
	v_cvt_pk_bf16_f32 v219, v66, v67
	v_lshl_add_u64 v[176:177], v[248:249], 0, s[42:43]
	global_store_dwordx2 v[176:177], v[218:219], off sc1
	v_fmamk_f32 v169, v170, 0x3b800000, v225
	v_mul_f32_e32 v220, 0x4b800000, v169
	v_cmp_gt_f32_e32 vcc, s30, v169
	v_lshlrev_b32_e32 v64, 16, v240
	v_and_b32_e32 v65, 0xffff0000, v240
	v_cndmask_b32_e32 v169, v169, v220, vcc
	v_rsq_f32_e32 v169, v169
	v_lshlrev_b32_e32 v66, 16, v241
	v_and_b32_e32 v67, 0xffff0000, v241
	v_mul_f32_e32 v220, 0x45800000, v169
	v_cndmask_b32_e32 v70, v169, v220, vcc
	v_pk_mul_f32 v[64:65], v[88:89], v[64:65]
	v_pk_mul_f32 v[66:67], v[90:91], v[66:67]
	v_pk_mul_f32 v[64:65], v[64:65], v[70:71] op_sel_hi:[1,0]
	v_pk_mul_f32 v[66:67], v[66:67], v[70:71] op_sel_hi:[1,0]
	v_pk_mul_f32 v[64:65], v[152:153], v[64:65]
	v_pk_mul_f32 v[66:67], v[154:155], v[66:67]
	s_add_u32 s42, s12, s36
	s_addc_u32 s43, s13, 0
	s_lshl_b64 s[42:43], s[42:43], 11
	v_cvt_pk_bf16_f32 v216, v64, v65
	v_cvt_pk_bf16_f32 v217, v66, v67
	v_lshl_add_u64 v[174:175], v[248:249], 0, s[42:43]
	global_store_dwordx2 v[174:175], v[216:217], off sc1
	v_fmamk_f32 v169, v171, 0x3b800000, v225
	v_mul_f32_e32 v220, 0x4b800000, v169
	v_cmp_gt_f32_e32 vcc, s30, v169
	v_lshlrev_b32_e32 v64, 16, v242
	v_and_b32_e32 v65, 0xffff0000, v242
	v_cndmask_b32_e32 v169, v169, v220, vcc
	v_rsq_f32_e32 v169, v169
	v_lshlrev_b32_e32 v66, 16, v243
	v_and_b32_e32 v67, 0xffff0000, v243
	v_mul_f32_e32 v220, 0x45800000, v169
	v_cndmask_b32_e32 v70, v169, v220, vcc
	v_pk_mul_f32 v[64:65], v[92:93], v[64:65]
	v_pk_mul_f32 v[66:67], v[94:95], v[66:67]
	v_pk_mul_f32 v[64:65], v[64:65], v[70:71] op_sel_hi:[1,0]
	v_pk_mul_f32 v[66:67], v[66:67], v[70:71] op_sel_hi:[1,0]
	v_pk_mul_f32 v[64:65], v[152:153], v[64:65]
	v_pk_mul_f32 v[66:67], v[154:155], v[66:67]
	s_add_u32 s42, s12, s35
	s_addc_u32 s43, s13, 0
	s_lshl_b64 s[42:43], s[42:43], 11
	v_cvt_pk_bf16_f32 v218, v64, v65
	v_cvt_pk_bf16_f32 v219, v66, v67
	v_lshl_add_u64 v[176:177], v[248:249], 0, s[42:43]
	global_store_dwordx2 v[176:177], v[218:219], off sc1
	v_fmamk_f32 v169, v172, 0x3b800000, v225
	v_mul_f32_e32 v220, 0x4b800000, v169
	v_cmp_gt_f32_e32 vcc, s30, v169
	v_lshlrev_b32_e32 v64, 16, v244
	v_and_b32_e32 v65, 0xffff0000, v244
	v_cndmask_b32_e32 v169, v169, v220, vcc
	v_rsq_f32_e32 v169, v169
	v_lshlrev_b32_e32 v66, 16, v245
	v_and_b32_e32 v67, 0xffff0000, v245
	v_mul_f32_e32 v220, 0x45800000, v169
	v_cndmask_b32_e32 v70, v169, v220, vcc
	v_pk_mul_f32 v[64:65], v[156:157], v[64:65]
	v_pk_mul_f32 v[66:67], v[158:159], v[66:67]
	v_pk_mul_f32 v[64:65], v[64:65], v[70:71] op_sel_hi:[1,0]
	v_pk_mul_f32 v[66:67], v[66:67], v[70:71] op_sel_hi:[1,0]
	v_pk_mul_f32 v[64:65], v[152:153], v[64:65]
	v_pk_mul_f32 v[66:67], v[154:155], v[66:67]
	s_add_u32 s42, s12, s21
	s_addc_u32 s43, s13, 0
	s_lshl_b64 s[42:43], s[42:43], 11
	v_cvt_pk_bf16_f32 v216, v64, v65
	v_cvt_pk_bf16_f32 v217, v66, v67
	v_lshl_add_u64 v[174:175], v[248:249], 0, s[42:43]
	global_store_dwordx2 v[174:175], v[216:217], off sc1
	v_fmamk_f32 v169, v173, 0x3b800000, v225
	v_mul_f32_e32 v220, 0x4b800000, v169
	v_cmp_gt_f32_e32 vcc, s30, v169
	v_lshlrev_b32_e32 v64, 16, v246
	v_and_b32_e32 v65, 0xffff0000, v246
	v_cndmask_b32_e32 v169, v169, v220, vcc
	v_rsq_f32_e32 v169, v169
	v_lshlrev_b32_e32 v66, 16, v247
	v_and_b32_e32 v67, 0xffff0000, v247
	v_mul_f32_e32 v220, 0x45800000, v169
	v_cndmask_b32_e32 v70, v169, v220, vcc
	v_pk_mul_f32 v[64:65], v[160:161], v[64:65]
	v_pk_mul_f32 v[66:67], v[162:163], v[66:67]
	v_pk_mul_f32 v[64:65], v[64:65], v[70:71] op_sel_hi:[1,0]
	v_pk_mul_f32 v[66:67], v[66:67], v[70:71] op_sel_hi:[1,0]
	v_pk_mul_f32 v[64:65], v[152:153], v[64:65]
	v_pk_mul_f32 v[66:67], v[154:155], v[66:67]
	s_add_u32 s42, s12, s20
	s_addc_u32 s43, s13, 0
	s_lshl_b64 s[42:43], s[42:43], 11
	v_cvt_pk_bf16_f32 v218, v64, v65
	v_cvt_pk_bf16_f32 v219, v66, v67
	v_lshl_add_u64 v[176:177], v[248:249], 0, s[42:43]
	global_store_dwordx2 v[176:177], v[218:219], off sc1
	s_nop 1
	v_readlane_b32 s56, v255, 4
	v_readlane_b32 s97, v254, 48
	v_readlane_b32 s92, v254, 51
	v_readlane_b32 s96, v254, 52
	v_readlane_b32 s57, v255, 5
	v_readlane_b32 s58, v255, 6
	v_readlane_b32 s59, v255, 7
	v_readlane_b32 s54, v254, 49
	v_readlane_b32 s55, v254, 50
	v_readlane_b32 s63, v254, 53
	v_readlane_b32 s34, v255, 11
	v_readlane_b32 s35, v255, 12
	s_barrier
